# combo2 + grouped-GEMM epilogue: scale and all 16 gate vectors loaded up front, counted waits
# speedup vs baseline: 1.0325x; 1.0087x over previous
; #define PG8_STAGE(bufoff, gbase, voff) do { _Pragma("unroll") for (int _i = 0; _i < 2; ++_i) \
;         __builtin_amdgcn_global_load_lds((const unsigned*)((const char*)(gbase) + (voff)[_i]), (LAS unsigned*)(lds + (bufoff) + ldsw + _i * 8192), 16, 0, 0); } while (0)
; #define PG8_LDA(dst, b, h) do { _Pragma("unroll") for (int m = 0; m < 4; ++m) _Pragma("unroll") for (int k = 0; k < 2; ++k) dst[m][k] = *(const LAS bf16x8*)(lds + PG8_SA(b, h) + aoff + m * 2048 + k * 1024); } while (0)
; #define PG8_LDB(dst, b, h) do { _Pragma("unroll") for (int n = 0; n < 2; ++n) _Pragma("unroll") for (int k = 0; k < 2; ++k) dst[n][k] = *(const LAS bf16x8*)(lds + PG8_SB(b, h) + boff + n * 2048 + k * 1024); } while (0)
; #define PG8_WAIT_V(n) asm volatile("s_waitcnt vmcnt(" #n ")" ::: "memory")
; #define PG8_WAIT_L(n) asm volatile("s_waitcnt lgkmcnt(" #n ")" ::: "memory")
; #define PG8_BAR __builtin_amdgcn_s_barrier()
; #define PG8_SCHED __builtin_amdgcn_sched_barrier(0)
; template <class Epi>
; __device__ __forceinline__ void gemm_phase(LAS unsigned char* lds, const Gemm g, const StaticOrder& S, const Epi& E) {
;     ...
;         const char* nA = has_next ? (const char*)g.A + (size_t)nxt.pm * tstepA + (size_t)nxt.pn * g.a_pn_step : cA; const char* nB = has_next ? (const char*)g.Bt + (size_t)nxt.pn * tstepB : cB;
; #pragma unroll 1
;         for (int t = 0; t < nt; t += 2) {
;             const bool last = (t == nt - 2);
;             const char* a1 = cA + (size_t)(t + 1) * kstep;
;             const char* a2 = last ? nA : cA + (size_t)(t + 2) * kstep; const char* b2 = last ? nB : cB + (size_t)(t + 2) * kstep;
;             const char* a3 = a2 + kstep; const char* b3 = b2 + kstep;
;             PG8_LDB(B0, 0, 0); PG8_SCHED; PG8_LDA(At, 0, 0); PG8_STAGE(PG8_SA(1, 1), a1 + hstepA, voffA);
;             PG8_WAIT_L(8); PG8_BAR; PG8_WAIT_L(0); PG8_MMA(0, 0, At, B0); PG8_BAR; PG8_SCHED;
;             PG8_LDB(B1, 0, 1); PG8_STAGE(PG8_SB(0, 0), b2, voffB);
;             PG8_BAR; PG8_WAIT_L(0); PG8_MMA(0, 1, At, B1); PG8_BAR;
;             PG8_LDA(At, 0, 1); PG8_STAGE(PG8_SA(0, 0), a2, voffA);
;             PG8_BAR; PG8_WAIT_L(0); PG8_MMA(1, 0, At, B0); PG8_BAR; PG8_SCHED;
;             PG8_STAGE(PG8_SB(0, 1), b2 + hstepB, voffB);
;             PG8_WAIT_V(6); PG8_BAR; PG8_MMA(1, 1, At, B1); PG8_BAR;
.LBB0_1392:
	s_add_u32 s66, s52, s58
	s_addc_u32 s67, s53, s59
	s_add_u32 s62, s66, 0x100
	s_addc_u32 s63, s67, 0
	s_and_b64 s[60:61], s[56:57], exec
	s_cselect_b32 s63, s0, s63
	s_cselect_b32 s62, s1, s62
	s_add_u32 s58, s46, s58
	s_addc_u32 s59, s47, s59
	s_add_u32 s58, s58, 0x100
	s_addc_u32 s59, s59, 0
	s_and_b64 s[56:57], s[56:57], exec
	s_cselect_b32 s65, s29, s59
	s_cselect_b32 s64, s37, s58
	s_add_u32 s66, s66, 0x40080
	s_addc_u32 s67, s67, 0
	s_add_i32 s92, s75, s34
	s_add_i32 m0, s35, 0xc000
	s_add_i32 s91, s35, 0xe000
	s_add_i32 s90, s92, 0x2000
	s_add_u32 s60, s64, 0x10000
	s_addc_u32 s61, s65, 0
	s_add_i32 s83, s76, s34
	ds_read_b128 v[140:143], v152
	ds_read_b128 v[144:147], v152 offset:1024
	ds_read_b128 v[156:159], v152 offset:2048
	ds_read_b128 v[160:163], v152 offset:3072
	s_add_i32 s82, s83, 0x2000
	s_add_i32 s81, 0, 0x18000
	s_add_u32 s58, s62, 0x40000
	s_addc_u32 s59, s63, 0
	s_add_i32 s80, s81, s34
	s_add_i32 s79, 0, 0x1c000
	s_add_i32 s78, s80, 0x2000
	s_add_u32 s56, s64, 0x10080
	s_addc_u32 s57, s65, 0
	s_add_i32 s89, s79, s34
	s_add_i32 s88, s89, 0x2000
	v_lshl_add_u64 v[198:199], s[66:67], 0, v[128:129]
	ds_read_b128 v[164:167], v153
	ds_read_b128 v[168:171], v153 offset:1024
	ds_read_b128 v[172:175], v153 offset:2048
	ds_read_b128 v[176:179], v153 offset:3072
	ds_read_b128 v[180:183], v153 offset:4096
	ds_read_b128 v[186:189], v153 offset:5120
	ds_read_b128 v[190:193], v153 offset:6144
	ds_read_b128 v[194:197], v153 offset:7168
	global_load_lds_dwordx4 v[198:199], off
	v_lshl_add_u64 v[198:199], s[66:67], 0, v[132:133]
	s_mov_b32 m0, s91
	s_nop 0
	global_load_lds_dwordx4 v[198:199], off
	s_waitcnt lgkmcnt(8)
	s_barrier
	s_waitcnt lgkmcnt(0)
	s_setprio 1
	s_waitcnt lgkmcnt(0)
	v_mfma_f32_16x16x32_bf16 v[124:127], v[140:143], v[164:167], v[124:127]
	v_mfma_f32_16x16x32_bf16 v[120:123], v[156:159], v[164:167], v[120:123]
	v_mfma_f32_16x16x32_bf16 v[108:111], v[140:143], v[172:175], v[108:111]
	v_mfma_f32_16x16x32_bf16 v[104:107], v[156:159], v[172:175], v[104:107]
	v_mfma_f32_16x16x32_bf16 v[92:95], v[140:143], v[180:183], v[92:95]
	v_mfma_f32_16x16x32_bf16 v[88:91], v[156:159], v[180:183], v[88:91]
	v_mfma_f32_16x16x32_bf16 v[76:79], v[140:143], v[190:193], v[76:79]
	v_mfma_f32_16x16x32_bf16 v[72:75], v[156:159], v[190:193], v[72:75]
	v_mfma_f32_16x16x32_bf16 v[124:127], v[144:147], v[168:171], v[124:127]
	v_mfma_f32_16x16x32_bf16 v[120:123], v[160:163], v[168:171], v[120:123]
	v_mfma_f32_16x16x32_bf16 v[108:111], v[144:147], v[176:179], v[108:111]
	v_mfma_f32_16x16x32_bf16 v[104:107], v[160:163], v[176:179], v[104:107]
	v_mfma_f32_16x16x32_bf16 v[92:95], v[144:147], v[186:189], v[92:95]
	v_mfma_f32_16x16x32_bf16 v[88:91], v[160:163], v[186:189], v[88:91]
	v_mfma_f32_16x16x32_bf16 v[76:79], v[144:147], v[194:197], v[76:79]
	v_mfma_f32_16x16x32_bf16 v[72:75], v[160:163], v[194:197], v[72:75]
	s_setprio 0
	s_barrier
	s_mov_b32 m0, s92
	v_lshl_add_u64 v[214:215], s[64:65], 0, v[130:131]
	ds_read_b128 v[198:201], v154
	ds_read_b128 v[202:205], v154 offset:1024
	ds_read_b128 v[206:209], v154 offset:2048
	ds_read_b128 v[210:213], v154 offset:3072
	global_load_lds_dwordx4 v[214:215], off
	v_lshl_add_u64 v[216:217], s[64:65], 0, v[134:135]
	s_mov_b32 m0, s90
	s_nop 0
	global_load_lds_dwordx4 v[216:217], off
	s_barrier
	s_waitcnt lgkmcnt(0)
	s_setprio 1
	s_waitcnt lgkmcnt(0)
	v_mfma_f32_16x16x32_bf16 v[116:119], v[198:201], v[164:167], v[116:119]
	v_mfma_f32_16x16x32_bf16 v[112:115], v[206:209], v[164:167], v[112:115]
	v_mfma_f32_16x16x32_bf16 v[100:103], v[198:201], v[172:175], v[100:103]
	v_mfma_f32_16x16x32_bf16 v[96:99], v[206:209], v[172:175], v[96:99]
	v_mfma_f32_16x16x32_bf16 v[84:87], v[198:201], v[180:183], v[84:87]
	v_mfma_f32_16x16x32_bf16 v[80:83], v[206:209], v[180:183], v[80:83]
	v_mfma_f32_16x16x32_bf16 v[68:71], v[198:201], v[190:193], v[68:71]
	v_mfma_f32_16x16x32_bf16 v[64:67], v[206:209], v[190:193], v[64:67]
	v_mfma_f32_16x16x32_bf16 v[116:119], v[202:205], v[168:171], v[116:119]
	v_mfma_f32_16x16x32_bf16 v[112:115], v[210:213], v[168:171], v[112:115]
	v_mfma_f32_16x16x32_bf16 v[100:103], v[202:205], v[176:179], v[100:103]
	v_mfma_f32_16x16x32_bf16 v[96:99], v[210:213], v[176:179], v[96:99]
	v_mfma_f32_16x16x32_bf16 v[84:87], v[202:205], v[186:189], v[84:87]
	v_mfma_f32_16x16x32_bf16 v[80:83], v[210:213], v[186:189], v[80:83]
	v_mfma_f32_16x16x32_bf16 v[68:71], v[202:205], v[194:197], v[68:71]
	v_mfma_f32_16x16x32_bf16 v[64:67], v[210:213], v[194:197], v[64:67]
	s_setprio 0
	s_mov_b32 m0, s35
	v_lshl_add_u64 v[218:219], s[62:63], 0, v[128:129]
	s_barrier
	ds_read_b128 v[164:167], v153 offset:16384
	ds_read_b128 v[168:171], v153 offset:17408
	ds_read_b128 v[172:175], v153 offset:18432
	ds_read_b128 v[176:179], v153 offset:19456
	ds_read_b128 v[180:183], v153 offset:20480
	ds_read_b128 v[186:189], v153 offset:21504
	ds_read_b128 v[190:193], v153 offset:22528
	ds_read_b128 v[194:197], v153 offset:23552
	global_load_lds_dwordx4 v[218:219], off
	v_lshl_add_u64 v[220:221], s[62:63], 0, v[132:133]
	s_mov_b32 m0, s43
	s_nop 0
	global_load_lds_dwordx4 v[220:221], off
	s_barrier
; #define PG8_STAGE(bufoff, gbase, voff) do { _Pragma("unroll") for (int _i = 0; _i < 2; ++_i) \
;         __builtin_amdgcn_global_load_lds((const unsigned*)((const char*)(gbase) + (voff)[_i]), (LAS unsigned*)(lds + (bufoff) + ldsw + _i * 8192), 16, 0, 0); } while (0)
; #define PG8_LDA(dst, b, h) do { _Pragma("unroll") for (int m = 0; m < 4; ++m) _Pragma("unroll") for (int k = 0; k < 2; ++k) dst[m][k] = *(const LAS bf16x8*)(lds + PG8_SA(b, h) + aoff + m * 2048 + k * 1024); } while (0)
; #define PG8_LDB(dst, b, h) do { _Pragma("unroll") for (int n = 0; n < 2; ++n) _Pragma("unroll") for (int k = 0; k < 2; ++k) dst[n][k] = *(const LAS bf16x8*)(lds + PG8_SB(b, h) + boff + n * 2048 + k * 1024); } while (0)
; #define PG8_MMA(ai, bj, At, Bt) do { __builtin_amdgcn_s_setprio(1); _Pragma("unroll") for (int m = 0; m < 4; ++m) _Pragma("unroll") for (int n = 0; n < 2; ++n) _Pragma("unroll") for (int k = 0; k < 2; ++k) \
;         acc[ai][bj][m][n] = __builtin_amdgcn_mfma_f32_16x16x32_bf16(Bt[n][k], At[m][k], acc[ai][bj][m][n], 0, 0, 0); __builtin_amdgcn_s_setprio(0); } while (0)
; #define PG8_WAIT_V(n) asm volatile("s_waitcnt vmcnt(" #n ")" ::: "memory")
; #define PG8_WAIT_L(n) asm volatile("s_waitcnt lgkmcnt(" #n ")" ::: "memory")
; #define PG8_BAR __builtin_amdgcn_s_barrier()
; #define PG8_SCHED __builtin_amdgcn_sched_barrier(0)
; template <class Epi>
; __device__ __forceinline__ void gemm_phase(LAS unsigned char* lds, const Gemm g, const StaticOrder& S, const Epi& E) {
;     ...
;             PG8_BAR; PG8_WAIT_L(0); PG8_MMA(1, 0, At, B0); PG8_BAR; PG8_SCHED;
;             PG8_STAGE(PG8_SB(0, 1), b2 + hstepB, voffB);
;             PG8_WAIT_V(6); PG8_BAR; PG8_MMA(1, 1, At, B1); PG8_BAR;
;             PG8_LDB(B0, 1, 0); PG8_SCHED; PG8_LDA(At, 1, 0); PG8_STAGE(PG8_SA(0, 1), a2 + hstepA, voffA);
;             PG8_WAIT_L(8); PG8_BAR; PG8_WAIT_L(0); PG8_MMA(0, 0, At, B0); PG8_BAR; PG8_SCHED;
;             PG8_LDB(B1, 1, 1); PG8_STAGE(PG8_SB(1, 0), b3, voffB);
;             PG8_BAR; PG8_WAIT_L(0); PG8_MMA(0, 1, At, B1); PG8_BAR;
	s_waitcnt lgkmcnt(0)
	s_setprio 1
	s_waitcnt lgkmcnt(0)
	v_mfma_f32_16x16x32_bf16 v[60:63], v[140:143], v[164:167], v[60:63]
	v_mfma_f32_16x16x32_bf16 v[56:59], v[156:159], v[164:167], v[56:59]
	v_mfma_f32_16x16x32_bf16 v[44:47], v[140:143], v[172:175], v[44:47]
	v_mfma_f32_16x16x32_bf16 v[40:43], v[156:159], v[172:175], v[40:43]
	v_mfma_f32_16x16x32_bf16 v[28:31], v[140:143], v[180:183], v[28:31]
	v_mfma_f32_16x16x32_bf16 v[24:27], v[156:159], v[180:183], v[24:27]
	v_mfma_f32_16x16x32_bf16 v[12:15], v[140:143], v[190:193], v[12:15]
	v_mfma_f32_16x16x32_bf16 v[8:11], v[156:159], v[190:193], v[8:11]
	v_mfma_f32_16x16x32_bf16 v[60:63], v[144:147], v[168:171], v[60:63]
	v_mfma_f32_16x16x32_bf16 v[56:59], v[160:163], v[168:171], v[56:59]
	v_mfma_f32_16x16x32_bf16 v[44:47], v[144:147], v[176:179], v[44:47]
	v_mfma_f32_16x16x32_bf16 v[40:43], v[160:163], v[176:179], v[40:43]
	v_mfma_f32_16x16x32_bf16 v[28:31], v[144:147], v[186:189], v[28:31]
	v_mfma_f32_16x16x32_bf16 v[24:27], v[160:163], v[186:189], v[24:27]
	v_mfma_f32_16x16x32_bf16 v[12:15], v[144:147], v[194:197], v[12:15]
	v_mfma_f32_16x16x32_bf16 v[8:11], v[160:163], v[194:197], v[8:11]
	s_setprio 0
	s_barrier
	s_mov_b32 m0, s83
	v_lshl_add_u64 v[140:141], s[60:61], 0, v[130:131]
	global_load_lds_dwordx4 v[140:141], off
	v_lshl_add_u64 v[140:141], s[60:61], 0, v[134:135]
	s_mov_b32 m0, s82
	s_nop 0
	global_load_lds_dwordx4 v[140:141], off
	s_waitcnt vmcnt(6)
	s_barrier
	s_setprio 1
	v_mfma_f32_16x16x32_bf16 v[52:55], v[198:201], v[164:167], v[52:55]
	v_mfma_f32_16x16x32_bf16 v[48:51], v[206:209], v[164:167], v[48:51]
	v_mfma_f32_16x16x32_bf16 v[36:39], v[198:201], v[172:175], v[36:39]
	v_mfma_f32_16x16x32_bf16 v[32:35], v[206:209], v[172:175], v[32:35]
	v_mfma_f32_16x16x32_bf16 v[20:23], v[198:201], v[180:183], v[20:23]
	v_mfma_f32_16x16x32_bf16 v[16:19], v[206:209], v[180:183], v[16:19]
	v_mfma_f32_16x16x32_bf16 v[4:7], v[198:201], v[190:193], v[4:7]
	v_mfma_f32_16x16x32_bf16 v[0:3], v[206:209], v[190:193], v[0:3]
	v_mfma_f32_16x16x32_bf16 v[52:55], v[202:205], v[168:171], v[52:55]
	v_mfma_f32_16x16x32_bf16 v[48:51], v[210:213], v[168:171], v[48:51]
	v_mfma_f32_16x16x32_bf16 v[36:39], v[202:205], v[176:179], v[36:39]
	v_mfma_f32_16x16x32_bf16 v[32:35], v[210:213], v[176:179], v[32:35]
	v_mfma_f32_16x16x32_bf16 v[20:23], v[202:205], v[186:189], v[20:23]
	v_mfma_f32_16x16x32_bf16 v[16:19], v[210:213], v[186:189], v[16:19]
	v_mfma_f32_16x16x32_bf16 v[4:7], v[202:205], v[194:197], v[4:7]
	v_mfma_f32_16x16x32_bf16 v[0:3], v[210:213], v[194:197], v[0:3]
	s_setprio 0
	v_add_u32_e32 v155, s81, v150
	s_barrier
	ds_read_b128 v[140:143], v155
	ds_read_b128 v[144:147], v155 offset:1024
	ds_read_b128 v[156:159], v155 offset:2048
	ds_read_b128 v[160:163], v155 offset:3072
	s_mov_b32 m0, s68
	v_lshl_add_u64 v[198:199], s[58:59], 0, v[128:129]
	ds_read_b128 v[164:167], v153 offset:32768
	ds_read_b128 v[168:171], v153 offset:33792
	ds_read_b128 v[172:175], v153 offset:34816
	ds_read_b128 v[176:179], v153 offset:35840
	ds_read_b128 v[180:183], v153 offset:36864
	ds_read_b128 v[186:189], v153 offset:37888
	ds_read_b128 v[190:193], v153 offset:38912
	ds_read_b128 v[194:197], v153 offset:39936
	global_load_lds_dwordx4 v[198:199], off
	v_lshl_add_u64 v[198:199], s[58:59], 0, v[132:133]
	s_mov_b32 m0, s69
	s_nop 0
	global_load_lds_dwordx4 v[198:199], off
	s_waitcnt lgkmcnt(8)
	s_barrier
	s_waitcnt lgkmcnt(0)
	s_setprio 1
	s_waitcnt lgkmcnt(0)
	v_mfma_f32_16x16x32_bf16 v[124:127], v[140:143], v[164:167], v[124:127]
	v_mfma_f32_16x16x32_bf16 v[120:123], v[156:159], v[164:167], v[120:123]
	v_mfma_f32_16x16x32_bf16 v[108:111], v[140:143], v[172:175], v[108:111]
	v_mfma_f32_16x16x32_bf16 v[104:107], v[156:159], v[172:175], v[104:107]
	v_mfma_f32_16x16x32_bf16 v[92:95], v[140:143], v[180:183], v[92:95]
	v_mfma_f32_16x16x32_bf16 v[88:91], v[156:159], v[180:183], v[88:91]
	v_mfma_f32_16x16x32_bf16 v[76:79], v[140:143], v[190:193], v[76:79]
	v_mfma_f32_16x16x32_bf16 v[72:75], v[156:159], v[190:193], v[72:75]
	v_mfma_f32_16x16x32_bf16 v[124:127], v[144:147], v[168:171], v[124:127]
	v_mfma_f32_16x16x32_bf16 v[120:123], v[160:163], v[168:171], v[120:123]
	v_mfma_f32_16x16x32_bf16 v[108:111], v[144:147], v[176:179], v[108:111]
	v_mfma_f32_16x16x32_bf16 v[104:107], v[160:163], v[176:179], v[104:107]
	v_mfma_f32_16x16x32_bf16 v[92:95], v[144:147], v[186:189], v[92:95]
	v_mfma_f32_16x16x32_bf16 v[88:91], v[160:163], v[186:189], v[88:91]
	v_mfma_f32_16x16x32_bf16 v[76:79], v[144:147], v[194:197], v[76:79]
	v_mfma_f32_16x16x32_bf16 v[72:75], v[160:163], v[194:197], v[72:75]
	s_setprio 0
	s_barrier
	s_mov_b32 m0, s80
	v_add_u32_e32 v155, s79, v150
	v_lshl_add_u64 v[214:215], v[214:215], 0, s[20:21]
	ds_read_b128 v[198:201], v155
	ds_read_b128 v[202:205], v155 offset:1024
	ds_read_b128 v[206:209], v155 offset:2048
	ds_read_b128 v[210:213], v155 offset:3072
	global_load_lds_dwordx4 v[214:215], off
	v_lshl_add_u64 v[214:215], v[216:217], 0, s[20:21]
	s_mov_b32 m0, s78
	s_nop 0
	global_load_lds_dwordx4 v[214:215], off
	s_barrier
; #define PG8_STAGE(bufoff, gbase, voff) do { _Pragma("unroll") for (int _i = 0; _i < 2; ++_i) \
;         __builtin_amdgcn_global_load_lds((const unsigned*)((const char*)(gbase) + (voff)[_i]), (LAS unsigned*)(lds + (bufoff) + ldsw + _i * 8192), 16, 0, 0); } while (0)
; #define PG8_LDA(dst, b, h) do { _Pragma("unroll") for (int m = 0; m < 4; ++m) _Pragma("unroll") for (int k = 0; k < 2; ++k) dst[m][k] = *(const LAS bf16x8*)(lds + PG8_SA(b, h) + aoff + m * 2048 + k * 1024); } while (0)
; #define PG8_MMA(ai, bj, At, Bt) do { __builtin_amdgcn_s_setprio(1); _Pragma("unroll") for (int m = 0; m < 4; ++m) _Pragma("unroll") for (int n = 0; n < 2; ++n) _Pragma("unroll") for (int k = 0; k < 2; ++k) \
;         acc[ai][bj][m][n] = __builtin_amdgcn_mfma_f32_16x16x32_bf16(Bt[n][k], At[m][k], acc[ai][bj][m][n], 0, 0, 0); __builtin_amdgcn_s_setprio(0); } while (0)
; #define PG8_WAIT_V(n) asm volatile("s_waitcnt vmcnt(" #n ")" ::: "memory")
; #define PG8_WAIT_L(n) asm volatile("s_waitcnt lgkmcnt(" #n ")" ::: "memory")
; #define PG8_BAR __builtin_amdgcn_s_barrier()
; #define PG8_SCHED __builtin_amdgcn_sched_barrier(0)
; template <class Epi>
; __device__ __forceinline__ void gemm_phase(LAS unsigned char* lds, const Gemm g, const StaticOrder& S, const Epi& E) {
;     ...
;             PG8_BAR; PG8_WAIT_L(0); PG8_MMA(0, 1, At, B1); PG8_BAR;
;             PG8_LDA(At, 1, 1); PG8_STAGE(PG8_SA(1, 0), a3, voffA);
;             PG8_BAR; PG8_WAIT_L(0); PG8_MMA(1, 0, At, B0); PG8_BAR; PG8_SCHED;
;             PG8_STAGE(PG8_SB(1, 1), b3 + hstepB, voffB);
;             PG8_WAIT_V(6); PG8_BAR; PG8_MMA(1, 1, At, B1); PG8_BAR;
	s_waitcnt lgkmcnt(0)
	s_setprio 1
	s_waitcnt lgkmcnt(0)
	v_mfma_f32_16x16x32_bf16 v[116:119], v[198:201], v[164:167], v[116:119]
	v_mfma_f32_16x16x32_bf16 v[112:115], v[206:209], v[164:167], v[112:115]
	v_mfma_f32_16x16x32_bf16 v[100:103], v[198:201], v[172:175], v[100:103]
	v_mfma_f32_16x16x32_bf16 v[96:99], v[206:209], v[172:175], v[96:99]
	v_mfma_f32_16x16x32_bf16 v[84:87], v[198:201], v[180:183], v[84:87]
	v_mfma_f32_16x16x32_bf16 v[80:83], v[206:209], v[180:183], v[80:83]
	v_mfma_f32_16x16x32_bf16 v[68:71], v[198:201], v[190:193], v[68:71]
	v_mfma_f32_16x16x32_bf16 v[64:67], v[206:209], v[190:193], v[64:67]
	v_mfma_f32_16x16x32_bf16 v[116:119], v[202:205], v[168:171], v[116:119]
	v_mfma_f32_16x16x32_bf16 v[112:115], v[210:213], v[168:171], v[112:115]
	v_mfma_f32_16x16x32_bf16 v[100:103], v[202:205], v[176:179], v[100:103]
	v_mfma_f32_16x16x32_bf16 v[96:99], v[210:213], v[176:179], v[96:99]
	v_mfma_f32_16x16x32_bf16 v[84:87], v[202:205], v[186:189], v[84:87]
	v_mfma_f32_16x16x32_bf16 v[80:83], v[210:213], v[186:189], v[80:83]
	v_mfma_f32_16x16x32_bf16 v[68:71], v[202:205], v[194:197], v[68:71]
	v_mfma_f32_16x16x32_bf16 v[64:67], v[210:213], v[194:197], v[64:67]
	s_setprio 0
	s_mov_b32 m0, s71
	v_lshl_add_u64 v[214:215], v[218:219], 0, s[20:21]
	s_barrier
	ds_read_b128 v[164:167], v153 offset:49152
	ds_read_b128 v[168:171], v153 offset:50176
	ds_read_b128 v[172:175], v153 offset:51200
	ds_read_b128 v[176:179], v153 offset:52224
	ds_read_b128 v[180:183], v153 offset:53248
	ds_read_b128 v[186:189], v153 offset:54272
	ds_read_b128 v[190:193], v153 offset:55296
	ds_read_b128 v[194:197], v153 offset:56320
	global_load_lds_dwordx4 v[214:215], off
	v_lshl_add_u64 v[214:215], v[220:221], 0, s[20:21]
	s_mov_b32 m0, s72
	s_nop 0
	global_load_lds_dwordx4 v[214:215], off
	s_barrier
	s_waitcnt lgkmcnt(0)
	s_setprio 1
	s_waitcnt lgkmcnt(0)
	v_mfma_f32_16x16x32_bf16 v[60:63], v[140:143], v[164:167], v[60:63]
	v_mfma_f32_16x16x32_bf16 v[56:59], v[156:159], v[164:167], v[56:59]
	v_mfma_f32_16x16x32_bf16 v[44:47], v[140:143], v[172:175], v[44:47]
	v_mfma_f32_16x16x32_bf16 v[40:43], v[156:159], v[172:175], v[40:43]
	v_mfma_f32_16x16x32_bf16 v[28:31], v[140:143], v[180:183], v[28:31]
	v_mfma_f32_16x16x32_bf16 v[24:27], v[156:159], v[180:183], v[24:27]
	v_mfma_f32_16x16x32_bf16 v[12:15], v[140:143], v[190:193], v[12:15]
	v_mfma_f32_16x16x32_bf16 v[8:11], v[156:159], v[190:193], v[8:11]
	v_mfma_f32_16x16x32_bf16 v[60:63], v[144:147], v[168:171], v[60:63]
	v_mfma_f32_16x16x32_bf16 v[56:59], v[160:163], v[168:171], v[56:59]
	v_mfma_f32_16x16x32_bf16 v[44:47], v[144:147], v[176:179], v[44:47]
	v_mfma_f32_16x16x32_bf16 v[40:43], v[160:163], v[176:179], v[40:43]
	v_mfma_f32_16x16x32_bf16 v[28:31], v[144:147], v[186:189], v[28:31]
	v_mfma_f32_16x16x32_bf16 v[24:27], v[160:163], v[186:189], v[24:27]
	v_mfma_f32_16x16x32_bf16 v[12:15], v[144:147], v[194:197], v[12:15]
	v_mfma_f32_16x16x32_bf16 v[8:11], v[160:163], v[194:197], v[8:11]
	s_setprio 0
	s_barrier
	s_mov_b32 m0, s89
	v_lshl_add_u64 v[140:141], s[56:57], 0, v[130:131]
	global_load_lds_dwordx4 v[140:141], off
	v_lshl_add_u64 v[140:141], s[56:57], 0, v[134:135]
	s_mov_b32 m0, s88
	s_nop 0
	global_load_lds_dwordx4 v[140:141], off
	s_waitcnt vmcnt(6)
	s_barrier
	s_setprio 1
	v_mfma_f32_16x16x32_bf16 v[52:55], v[198:201], v[164:167], v[52:55]
	v_mfma_f32_16x16x32_bf16 v[48:51], v[206:209], v[164:167], v[48:51]
	v_mfma_f32_16x16x32_bf16 v[36:39], v[198:201], v[172:175], v[36:39]
	v_mfma_f32_16x16x32_bf16 v[32:35], v[206:209], v[172:175], v[32:35]
	v_mfma_f32_16x16x32_bf16 v[20:23], v[198:201], v[180:183], v[20:23]
	v_mfma_f32_16x16x32_bf16 v[16:19], v[206:209], v[180:183], v[16:19]
	v_mfma_f32_16x16x32_bf16 v[4:7], v[198:201], v[190:193], v[4:7]
	v_mfma_f32_16x16x32_bf16 v[0:3], v[206:209], v[190:193], v[0:3]
	v_mfma_f32_16x16x32_bf16 v[52:55], v[202:205], v[168:171], v[52:55]
	v_mfma_f32_16x16x32_bf16 v[48:51], v[210:213], v[168:171], v[48:51]
	v_mfma_f32_16x16x32_bf16 v[36:39], v[202:205], v[176:179], v[36:39]
	v_mfma_f32_16x16x32_bf16 v[32:35], v[210:213], v[176:179], v[32:35]
	v_mfma_f32_16x16x32_bf16 v[20:23], v[202:205], v[186:189], v[20:23]
	v_mfma_f32_16x16x32_bf16 v[16:19], v[210:213], v[186:189], v[16:19]
	v_mfma_f32_16x16x32_bf16 v[4:7], v[202:205], v[194:197], v[4:7]
	v_mfma_f32_16x16x32_bf16 v[0:3], v[210:213], v[194:197], v[0:3]
	s_setprio 0
	s_andn2_b64 vcc, exec, s[54:55]
	s_mov_b64 s[56:57], -1
	s_mov_b64 s[54:55], 0
	s_mov_b64 s[58:59], 0x100
	s_barrier
	s_cbranch_vccz .LBB0_1392
; __device__ __forceinline__ unsigned cvt_pk_bf16(float lo, float hi) { const f32v2_t v = {lo, hi}; const bf16v2_t r = __builtin_convertvector(v, bf16v2_t); return __builtin_bit_cast(unsigned, r); }
; __device__ __forceinline__ float bf2f(short b) { return __uint_as_float(((unsigned)(unsigned short)b) << 16); }
;     __device__ __forceinline__ void operator()(const f32x4 (&acc)[2][2][4][2], const Unit& u, int wr, int wc, int fr, int fq) const {
;     ...
;             for (int m = 0; m < 4; ++m) { const size_t ro = (size_t)(row0 + ai * HALF + m * 16) * DM + col0;
; #pragma unroll
;                 for (int bj = 0; bj < 2; ++bj) { const bf16x8 gv = *(const bf16x8*)(SG + ro + bj * HALF);
;                     const f32x4 v0 = acc[ai][bj][m][0] * *(const f32x4*)(scale + col0 + bj * HALF), v1 = acc[ai][bj][m][1] * *(const f32x4*)(scale + col0 + bj * HALF + 4);
;                     u32x4 w; w.x = cvt_pk_bf16(v0[0] * bf2f(gv[0]), v0[1] * bf2f(gv[1])); w.y = cvt_pk_bf16(v0[2] * bf2f(gv[2]), v0[3] * bf2f(gv[3]));
;                     w.z = cvt_pk_bf16(v1[0] * bf2f(gv[4]), v1[1] * bf2f(gv[5])); w.w = cvt_pk_bf16(v1[2] * bf2f(gv[6]), v1[3] * bf2f(gv[7]));
;                     *(u32x4*)(O + ro + bj * HALF) = w; } }
	v_lshl_add_u32 v146, s42, 8, v149
	v_lshl_or_b32 v144, s77, 8, v151
	v_ashrrev_i32_e32 v147, 31, v146
	v_ashrrev_i32_e32 v145, 31, v144
	v_lshlrev_b64 v[142:143], 10, v[146:147]
	v_lshl_add_u64 v[142:143], v[142:143], 0, v[144:145]
	v_lshlrev_b64 v[142:143], 1, v[142:143]
	v_lshl_add_u64 v[140:141], v[144:145], 2, s[44:45]
	s_and_b64 vcc, exec, s[2:3]
	s_mov_b32 s77, s28
	s_mov_b32 s42, s36
	s_mov_b64 s[46:47], s[40:41]
	s_mov_b64 s[52:53], s[38:39]
	s_mov_b64 s[60:61], 0x8000
	s_mov_b64 s[62:63], 0x28000
	global_load_dwordx4 v[222:225], v[140:141], off
	global_load_dwordx4 v[226:229], v[140:141], off offset:16
	global_load_dwordx4 v[230:233], v[140:141], off offset:512
	global_load_dwordx4 v[234:237], v[140:141], off offset:528
	v_lshl_add_u64 v[144:145], s[10:11], 0, v[142:143]
	global_load_dwordx4 v[156:159], v[144:145], off
	global_load_dwordx4 v[160:163], v[144:145], off offset:256
	v_lshl_add_u64 v[144:145], v[144:145], 0, s[60:61]
	global_load_dwordx4 v[164:167], v[144:145], off
	global_load_dwordx4 v[168:171], v[144:145], off offset:256
	v_lshl_add_u64 v[144:145], v[144:145], 0, s[60:61]
	global_load_dwordx4 v[172:175], v[144:145], off
	global_load_dwordx4 v[176:179], v[144:145], off offset:256
	v_lshl_add_u64 v[144:145], v[144:145], 0, s[60:61]
	global_load_dwordx4 v[180:183], v[144:145], off
	global_load_dwordx4 v[186:189], v[144:145], off offset:256
	v_lshl_add_u64 v[144:145], v[144:145], 0, s[62:63]
	global_load_dwordx4 v[190:193], v[144:145], off
	global_load_dwordx4 v[194:197], v[144:145], off offset:256
	v_lshl_add_u64 v[144:145], v[144:145], 0, s[60:61]
	global_load_dwordx4 v[198:201], v[144:145], off
	global_load_dwordx4 v[202:205], v[144:145], off offset:256
	v_lshl_add_u64 v[144:145], v[144:145], 0, s[60:61]
	global_load_dwordx4 v[206:209], v[144:145], off
	global_load_dwordx4 v[210:213], v[144:145], off offset:256
	v_lshl_add_u64 v[144:145], v[144:145], 0, s[60:61]
	global_load_dwordx4 v[214:217], v[144:145], off
	global_load_dwordx4 v[218:221], v[144:145], off offset:256
	v_lshl_add_u64 v[144:145], s[12:13], 0, v[142:143]
	s_waitcnt vmcnt(15)
	v_pk_mul_f32 v[124:125], v[124:125], v[222:223]
	v_pk_mul_f32 v[126:127], v[126:127], v[224:225]
	v_pk_mul_f32 v[120:121], v[120:121], v[226:227]
	v_pk_mul_f32 v[122:123], v[122:123], v[228:229]
	v_and_b32_e32 v239, 0xffff0000, v156
	v_lshlrev_b32_e32 v238, 16, v156
	v_and_b32_e32 v241, 0xffff0000, v157
	v_lshlrev_b32_e32 v240, 16, v157
	v_and_b32_e32 v243, 0xffff0000, v158
	v_lshlrev_b32_e32 v242, 16, v158
	v_and_b32_e32 v245, 0xffff0000, v159
	v_lshlrev_b32_e32 v244, 16, v159
	v_pk_mul_f32 v[124:125], v[124:125], v[238:239]
	v_pk_mul_f32 v[126:127], v[126:127], v[240:241]
	v_pk_mul_f32 v[120:121], v[120:121], v[242:243]
	v_pk_mul_f32 v[122:123], v[122:123], v[244:245]
	v_cvt_pk_bf16_f32 v156, v124, v125
	v_cvt_pk_bf16_f32 v157, v126, v127
	v_cvt_pk_bf16_f32 v158, v120, v121
	v_cvt_pk_bf16_f32 v159, v122, v123
	global_store_dwordx4 v[144:145], v[156:159], off
	s_waitcnt vmcnt(15)
	v_pk_mul_f32 v[116:117], v[116:117], v[230:231]
	v_pk_mul_f32 v[118:119], v[118:119], v[232:233]
	v_pk_mul_f32 v[112:113], v[112:113], v[234:235]
	v_pk_mul_f32 v[114:115], v[114:115], v[236:237]
	v_and_b32_e32 v239, 0xffff0000, v160
	v_lshlrev_b32_e32 v238, 16, v160
	v_and_b32_e32 v241, 0xffff0000, v161
	v_lshlrev_b32_e32 v240, 16, v161
	v_and_b32_e32 v243, 0xffff0000, v162
	v_lshlrev_b32_e32 v242, 16, v162
	v_and_b32_e32 v245, 0xffff0000, v163
	v_lshlrev_b32_e32 v244, 16, v163
	v_pk_mul_f32 v[116:117], v[116:117], v[238:239]
	v_pk_mul_f32 v[118:119], v[118:119], v[240:241]
	v_pk_mul_f32 v[112:113], v[112:113], v[242:243]
	v_pk_mul_f32 v[114:115], v[114:115], v[244:245]
	v_cvt_pk_bf16_f32 v160, v116, v117
	v_cvt_pk_bf16_f32 v161, v118, v119
	v_cvt_pk_bf16_f32 v162, v112, v113
	v_cvt_pk_bf16_f32 v163, v114, v115
	global_store_dwordx4 v[144:145], v[160:163], off offset:256
	v_lshl_add_u64 v[144:145], v[144:145], 0, s[60:61]
	s_waitcnt vmcnt(15)
	v_pk_mul_f32 v[108:109], v[108:109], v[222:223]
	v_pk_mul_f32 v[110:111], v[110:111], v[224:225]
	v_pk_mul_f32 v[104:105], v[104:105], v[226:227]
	v_pk_mul_f32 v[106:107], v[106:107], v[228:229]
	v_and_b32_e32 v239, 0xffff0000, v164
	v_lshlrev_b32_e32 v238, 16, v164
	v_and_b32_e32 v241, 0xffff0000, v165
	v_lshlrev_b32_e32 v240, 16, v165
	v_and_b32_e32 v243, 0xffff0000, v166
	v_lshlrev_b32_e32 v242, 16, v166
	v_and_b32_e32 v245, 0xffff0000, v167
	v_lshlrev_b32_e32 v244, 16, v167
	v_pk_mul_f32 v[108:109], v[108:109], v[238:239]
	v_pk_mul_f32 v[110:111], v[110:111], v[240:241]
	v_pk_mul_f32 v[104:105], v[104:105], v[242:243]
	v_pk_mul_f32 v[106:107], v[106:107], v[244:245]
	v_cvt_pk_bf16_f32 v164, v108, v109
	v_cvt_pk_bf16_f32 v165, v110, v111
	v_cvt_pk_bf16_f32 v166, v104, v105
	v_cvt_pk_bf16_f32 v167, v106, v107
	global_store_dwordx4 v[144:145], v[164:167], off
	s_waitcnt vmcnt(15)
	v_pk_mul_f32 v[100:101], v[100:101], v[230:231]
	v_pk_mul_f32 v[102:103], v[102:103], v[232:233]
	v_pk_mul_f32 v[96:97], v[96:97], v[234:235]
	v_pk_mul_f32 v[98:99], v[98:99], v[236:237]
	v_and_b32_e32 v239, 0xffff0000, v168
	v_lshlrev_b32_e32 v238, 16, v168
	v_and_b32_e32 v241, 0xffff0000, v169
	v_lshlrev_b32_e32 v240, 16, v169
	v_and_b32_e32 v243, 0xffff0000, v170
	v_lshlrev_b32_e32 v242, 16, v170
	v_and_b32_e32 v245, 0xffff0000, v171
	v_lshlrev_b32_e32 v244, 16, v171
	v_pk_mul_f32 v[100:101], v[100:101], v[238:239]
	v_pk_mul_f32 v[102:103], v[102:103], v[240:241]
	v_pk_mul_f32 v[96:97], v[96:97], v[242:243]
	v_pk_mul_f32 v[98:99], v[98:99], v[244:245]
	v_cvt_pk_bf16_f32 v168, v100, v101
	v_cvt_pk_bf16_f32 v169, v102, v103
	v_cvt_pk_bf16_f32 v170, v96, v97
	v_cvt_pk_bf16_f32 v171, v98, v99
	global_store_dwordx4 v[144:145], v[168:171], off offset:256
	v_lshl_add_u64 v[144:145], v[144:145], 0, s[60:61]
	s_waitcnt vmcnt(15)
; __device__ __forceinline__ unsigned cvt_pk_bf16(float lo, float hi) { const f32v2_t v = {lo, hi}; const bf16v2_t r = __builtin_convertvector(v, bf16v2_t); return __builtin_bit_cast(unsigned, r); }
; __device__ __forceinline__ float bf2f(short b) { return __uint_as_float(((unsigned)(unsigned short)b) << 16); }
;     __device__ __forceinline__ void operator()(const f32x4 (&acc)[2][2][4][2], const Unit& u, int wr, int wc, int fr, int fq) const {
;     ...
;             for (int m = 0; m < 4; ++m) { const size_t ro = (size_t)(row0 + ai * HALF + m * 16) * DM + col0;
; #pragma unroll
;                 for (int bj = 0; bj < 2; ++bj) { const bf16x8 gv = *(const bf16x8*)(SG + ro + bj * HALF);
;                     const f32x4 v0 = acc[ai][bj][m][0] * *(const f32x4*)(scale + col0 + bj * HALF), v1 = acc[ai][bj][m][1] * *(const f32x4*)(scale + col0 + bj * HALF + 4);
;                     u32x4 w; w.x = cvt_pk_bf16(v0[0] * bf2f(gv[0]), v0[1] * bf2f(gv[1])); w.y = cvt_pk_bf16(v0[2] * bf2f(gv[2]), v0[3] * bf2f(gv[3]));
;                     w.z = cvt_pk_bf16(v1[0] * bf2f(gv[4]), v1[1] * bf2f(gv[5])); w.w = cvt_pk_bf16(v1[2] * bf2f(gv[6]), v1[3] * bf2f(gv[7]));
;                     *(u32x4*)(O + ro + bj * HALF) = w; } }
	v_pk_mul_f32 v[92:93], v[92:93], v[222:223]
	v_pk_mul_f32 v[94:95], v[94:95], v[224:225]
	v_pk_mul_f32 v[88:89], v[88:89], v[226:227]
	v_pk_mul_f32 v[90:91], v[90:91], v[228:229]
	v_and_b32_e32 v239, 0xffff0000, v172
	v_lshlrev_b32_e32 v238, 16, v172
	v_and_b32_e32 v241, 0xffff0000, v173
	v_lshlrev_b32_e32 v240, 16, v173
	v_and_b32_e32 v243, 0xffff0000, v174
	v_lshlrev_b32_e32 v242, 16, v174
	v_and_b32_e32 v245, 0xffff0000, v175
	v_lshlrev_b32_e32 v244, 16, v175
	v_pk_mul_f32 v[92:93], v[92:93], v[238:239]
	v_pk_mul_f32 v[94:95], v[94:95], v[240:241]
	v_pk_mul_f32 v[88:89], v[88:89], v[242:243]
	v_pk_mul_f32 v[90:91], v[90:91], v[244:245]
	v_cvt_pk_bf16_f32 v172, v92, v93
	v_cvt_pk_bf16_f32 v173, v94, v95
	v_cvt_pk_bf16_f32 v174, v88, v89
	v_cvt_pk_bf16_f32 v175, v90, v91
	global_store_dwordx4 v[144:145], v[172:175], off
	s_waitcnt vmcnt(15)
	v_pk_mul_f32 v[84:85], v[84:85], v[230:231]
	v_pk_mul_f32 v[86:87], v[86:87], v[232:233]
	v_pk_mul_f32 v[80:81], v[80:81], v[234:235]
	v_pk_mul_f32 v[82:83], v[82:83], v[236:237]
	v_and_b32_e32 v239, 0xffff0000, v176
	v_lshlrev_b32_e32 v238, 16, v176
	v_and_b32_e32 v241, 0xffff0000, v177
	v_lshlrev_b32_e32 v240, 16, v177
	v_and_b32_e32 v243, 0xffff0000, v178
	v_lshlrev_b32_e32 v242, 16, v178
	v_and_b32_e32 v245, 0xffff0000, v179
	v_lshlrev_b32_e32 v244, 16, v179
	v_pk_mul_f32 v[84:85], v[84:85], v[238:239]
	v_pk_mul_f32 v[86:87], v[86:87], v[240:241]
	v_pk_mul_f32 v[80:81], v[80:81], v[242:243]
	v_pk_mul_f32 v[82:83], v[82:83], v[244:245]
	v_cvt_pk_bf16_f32 v176, v84, v85
	v_cvt_pk_bf16_f32 v177, v86, v87
	v_cvt_pk_bf16_f32 v178, v80, v81
	v_cvt_pk_bf16_f32 v179, v82, v83
	global_store_dwordx4 v[144:145], v[176:179], off offset:256
	v_lshl_add_u64 v[144:145], v[144:145], 0, s[60:61]
	s_waitcnt vmcnt(15)
	v_pk_mul_f32 v[76:77], v[76:77], v[222:223]
	v_pk_mul_f32 v[78:79], v[78:79], v[224:225]
	v_pk_mul_f32 v[72:73], v[72:73], v[226:227]
	v_pk_mul_f32 v[74:75], v[74:75], v[228:229]
	v_and_b32_e32 v239, 0xffff0000, v180
	v_lshlrev_b32_e32 v238, 16, v180
	v_and_b32_e32 v241, 0xffff0000, v181
	v_lshlrev_b32_e32 v240, 16, v181
	v_and_b32_e32 v243, 0xffff0000, v182
	v_lshlrev_b32_e32 v242, 16, v182
	v_and_b32_e32 v245, 0xffff0000, v183
	v_lshlrev_b32_e32 v244, 16, v183
	v_pk_mul_f32 v[76:77], v[76:77], v[238:239]
	v_pk_mul_f32 v[78:79], v[78:79], v[240:241]
	v_pk_mul_f32 v[72:73], v[72:73], v[242:243]
	v_pk_mul_f32 v[74:75], v[74:75], v[244:245]
	v_cvt_pk_bf16_f32 v180, v76, v77
	v_cvt_pk_bf16_f32 v181, v78, v79
	v_cvt_pk_bf16_f32 v182, v72, v73
	v_cvt_pk_bf16_f32 v183, v74, v75
	global_store_dwordx4 v[144:145], v[180:183], off
	s_waitcnt vmcnt(15)
	v_pk_mul_f32 v[68:69], v[68:69], v[230:231]
	v_pk_mul_f32 v[70:71], v[70:71], v[232:233]
	v_pk_mul_f32 v[64:65], v[64:65], v[234:235]
	v_pk_mul_f32 v[66:67], v[66:67], v[236:237]
	v_and_b32_e32 v239, 0xffff0000, v186
	v_lshlrev_b32_e32 v238, 16, v186
	v_and_b32_e32 v241, 0xffff0000, v187
	v_lshlrev_b32_e32 v240, 16, v187
	v_and_b32_e32 v243, 0xffff0000, v188
	v_lshlrev_b32_e32 v242, 16, v188
	v_and_b32_e32 v245, 0xffff0000, v189
	v_lshlrev_b32_e32 v244, 16, v189
	v_pk_mul_f32 v[68:69], v[68:69], v[238:239]
	v_pk_mul_f32 v[70:71], v[70:71], v[240:241]
	v_pk_mul_f32 v[64:65], v[64:65], v[242:243]
	v_pk_mul_f32 v[66:67], v[66:67], v[244:245]
	v_cvt_pk_bf16_f32 v186, v68, v69
	v_cvt_pk_bf16_f32 v187, v70, v71
	v_cvt_pk_bf16_f32 v188, v64, v65
	v_cvt_pk_bf16_f32 v189, v66, v67
	global_store_dwordx4 v[144:145], v[186:189], off offset:256
	v_lshl_add_u64 v[144:145], v[144:145], 0, s[62:63]
	s_waitcnt vmcnt(15)
	v_pk_mul_f32 v[60:61], v[60:61], v[222:223]
	v_pk_mul_f32 v[62:63], v[62:63], v[224:225]
	v_pk_mul_f32 v[56:57], v[56:57], v[226:227]
	v_pk_mul_f32 v[58:59], v[58:59], v[228:229]
	v_and_b32_e32 v239, 0xffff0000, v190
	v_lshlrev_b32_e32 v238, 16, v190
	v_and_b32_e32 v241, 0xffff0000, v191
	v_lshlrev_b32_e32 v240, 16, v191
	v_and_b32_e32 v243, 0xffff0000, v192
	v_lshlrev_b32_e32 v242, 16, v192
	v_and_b32_e32 v245, 0xffff0000, v193
	v_lshlrev_b32_e32 v244, 16, v193
	v_pk_mul_f32 v[60:61], v[60:61], v[238:239]
	v_pk_mul_f32 v[62:63], v[62:63], v[240:241]
	v_pk_mul_f32 v[56:57], v[56:57], v[242:243]
	v_pk_mul_f32 v[58:59], v[58:59], v[244:245]
	v_cvt_pk_bf16_f32 v190, v60, v61
	v_cvt_pk_bf16_f32 v191, v62, v63
	v_cvt_pk_bf16_f32 v192, v56, v57
	v_cvt_pk_bf16_f32 v193, v58, v59
	global_store_dwordx4 v[144:145], v[190:193], off
	s_waitcnt vmcnt(15)
	v_pk_mul_f32 v[52:53], v[52:53], v[230:231]
	v_pk_mul_f32 v[54:55], v[54:55], v[232:233]
	v_pk_mul_f32 v[48:49], v[48:49], v[234:235]
	v_pk_mul_f32 v[50:51], v[50:51], v[236:237]
	v_and_b32_e32 v239, 0xffff0000, v194
	v_lshlrev_b32_e32 v238, 16, v194
	v_and_b32_e32 v241, 0xffff0000, v195
	v_lshlrev_b32_e32 v240, 16, v195
	v_and_b32_e32 v243, 0xffff0000, v196
	v_lshlrev_b32_e32 v242, 16, v196
	v_and_b32_e32 v245, 0xffff0000, v197
	v_lshlrev_b32_e32 v244, 16, v197
	v_pk_mul_f32 v[52:53], v[52:53], v[238:239]
	v_pk_mul_f32 v[54:55], v[54:55], v[240:241]
	v_pk_mul_f32 v[48:49], v[48:49], v[242:243]
	v_pk_mul_f32 v[50:51], v[50:51], v[244:245]
	v_cvt_pk_bf16_f32 v194, v52, v53
	v_cvt_pk_bf16_f32 v195, v54, v55
	v_cvt_pk_bf16_f32 v196, v48, v49
	v_cvt_pk_bf16_f32 v197, v50, v51
	global_store_dwordx4 v[144:145], v[194:197], off offset:256
	v_lshl_add_u64 v[144:145], v[144:145], 0, s[60:61]
	s_waitcnt vmcnt(15)
; __device__ __forceinline__ unsigned cvt_pk_bf16(float lo, float hi) { const f32v2_t v = {lo, hi}; const bf16v2_t r = __builtin_convertvector(v, bf16v2_t); return __builtin_bit_cast(unsigned, r); }
; __device__ __forceinline__ float bf2f(short b) { return __uint_as_float(((unsigned)(unsigned short)b) << 16); }
; #define PG8_WAIT_V(n) asm volatile("s_waitcnt vmcnt(" #n ")" ::: "memory")
; #define PG8_BAR __builtin_amdgcn_s_barrier()
; template <class Epi>
; __device__ __forceinline__ void gemm_phase(LAS unsigned char* lds, const Gemm g, const StaticOrder& S, const Epi& E) {
;     ...
;         if (!has_next) break;
; #pragma unroll
;         for (int a = 0; a < 2; ++a)
; #pragma unroll
;             for (int b = 0; b < 2; ++b)
; #pragma unroll
;                 for (int m = 0; m < 4; ++m)
; #pragma unroll
;                     for (int n = 0; n < 2; ++n) acc[a][b][m][n] = (f32x4){0.f, 0.f, 0.f, 0.f};
;         cur = nxt; cA = nA; cB = nB; ++ui;
;     }
;     PG8_WAIT_V(0);
;     if (wr == 0) PG8_BAR;
;     PG8_BAR;
;     __device__ __forceinline__ void operator()(const f32x4 (&acc)[2][2][4][2], const Unit& u, int wr, int wc, int fr, int fq) const {
;     ...
;             for (int m = 0; m < 4; ++m) { const size_t ro = (size_t)(row0 + ai * HALF + m * 16) * DM + col0;
; #pragma unroll
;                 for (int bj = 0; bj < 2; ++bj) { const bf16x8 gv = *(const bf16x8*)(SG + ro + bj * HALF);
;                     const f32x4 v0 = acc[ai][bj][m][0] * *(const f32x4*)(scale + col0 + bj * HALF), v1 = acc[ai][bj][m][1] * *(const f32x4*)(scale + col0 + bj * HALF + 4);
;                     u32x4 w; w.x = cvt_pk_bf16(v0[0] * bf2f(gv[0]), v0[1] * bf2f(gv[1])); w.y = cvt_pk_bf16(v0[2] * bf2f(gv[2]), v0[3] * bf2f(gv[3]));
;                     w.z = cvt_pk_bf16(v1[0] * bf2f(gv[4]), v1[1] * bf2f(gv[5])); w.w = cvt_pk_bf16(v1[2] * bf2f(gv[6]), v1[3] * bf2f(gv[7]));
;                     *(u32x4*)(O + ro + bj * HALF) = w; } }
	v_pk_mul_f32 v[44:45], v[44:45], v[222:223]
	v_pk_mul_f32 v[46:47], v[46:47], v[224:225]
	v_pk_mul_f32 v[40:41], v[40:41], v[226:227]
	v_pk_mul_f32 v[42:43], v[42:43], v[228:229]
	v_and_b32_e32 v239, 0xffff0000, v198
	v_lshlrev_b32_e32 v238, 16, v198
	v_and_b32_e32 v241, 0xffff0000, v199
	v_lshlrev_b32_e32 v240, 16, v199
	v_and_b32_e32 v243, 0xffff0000, v200
	v_lshlrev_b32_e32 v242, 16, v200
	v_and_b32_e32 v245, 0xffff0000, v201
	v_lshlrev_b32_e32 v244, 16, v201
	v_pk_mul_f32 v[44:45], v[44:45], v[238:239]
	v_pk_mul_f32 v[46:47], v[46:47], v[240:241]
	v_pk_mul_f32 v[40:41], v[40:41], v[242:243]
	v_pk_mul_f32 v[42:43], v[42:43], v[244:245]
	v_cvt_pk_bf16_f32 v198, v44, v45
	v_cvt_pk_bf16_f32 v199, v46, v47
	v_cvt_pk_bf16_f32 v200, v40, v41
	v_cvt_pk_bf16_f32 v201, v42, v43
	global_store_dwordx4 v[144:145], v[198:201], off
	s_waitcnt vmcnt(15)
	v_pk_mul_f32 v[36:37], v[36:37], v[230:231]
	v_pk_mul_f32 v[38:39], v[38:39], v[232:233]
	v_pk_mul_f32 v[32:33], v[32:33], v[234:235]
	v_pk_mul_f32 v[34:35], v[34:35], v[236:237]
	v_and_b32_e32 v239, 0xffff0000, v202
	v_lshlrev_b32_e32 v238, 16, v202
	v_and_b32_e32 v241, 0xffff0000, v203
	v_lshlrev_b32_e32 v240, 16, v203
	v_and_b32_e32 v243, 0xffff0000, v204
	v_lshlrev_b32_e32 v242, 16, v204
	v_and_b32_e32 v245, 0xffff0000, v205
	v_lshlrev_b32_e32 v244, 16, v205
	v_pk_mul_f32 v[36:37], v[36:37], v[238:239]
	v_pk_mul_f32 v[38:39], v[38:39], v[240:241]
	v_pk_mul_f32 v[32:33], v[32:33], v[242:243]
	v_pk_mul_f32 v[34:35], v[34:35], v[244:245]
	v_cvt_pk_bf16_f32 v202, v36, v37
	v_cvt_pk_bf16_f32 v203, v38, v39
	v_cvt_pk_bf16_f32 v204, v32, v33
	v_cvt_pk_bf16_f32 v205, v34, v35
	global_store_dwordx4 v[144:145], v[202:205], off offset:256
	v_lshl_add_u64 v[144:145], v[144:145], 0, s[60:61]
	s_waitcnt vmcnt(15)
	v_pk_mul_f32 v[28:29], v[28:29], v[222:223]
	v_pk_mul_f32 v[30:31], v[30:31], v[224:225]
	v_pk_mul_f32 v[24:25], v[24:25], v[226:227]
	v_pk_mul_f32 v[26:27], v[26:27], v[228:229]
	v_and_b32_e32 v239, 0xffff0000, v206
	v_lshlrev_b32_e32 v238, 16, v206
	v_and_b32_e32 v241, 0xffff0000, v207
	v_lshlrev_b32_e32 v240, 16, v207
	v_and_b32_e32 v243, 0xffff0000, v208
	v_lshlrev_b32_e32 v242, 16, v208
	v_and_b32_e32 v245, 0xffff0000, v209
	v_lshlrev_b32_e32 v244, 16, v209
	v_pk_mul_f32 v[28:29], v[28:29], v[238:239]
	v_pk_mul_f32 v[30:31], v[30:31], v[240:241]
	v_pk_mul_f32 v[24:25], v[24:25], v[242:243]
	v_pk_mul_f32 v[26:27], v[26:27], v[244:245]
	v_cvt_pk_bf16_f32 v206, v28, v29
	v_cvt_pk_bf16_f32 v207, v30, v31
	v_cvt_pk_bf16_f32 v208, v24, v25
	v_cvt_pk_bf16_f32 v209, v26, v27
	global_store_dwordx4 v[144:145], v[206:209], off
	s_waitcnt vmcnt(15)
	v_pk_mul_f32 v[20:21], v[20:21], v[230:231]
	v_pk_mul_f32 v[22:23], v[22:23], v[232:233]
	v_pk_mul_f32 v[16:17], v[16:17], v[234:235]
	v_pk_mul_f32 v[18:19], v[18:19], v[236:237]
	v_and_b32_e32 v239, 0xffff0000, v210
	v_lshlrev_b32_e32 v238, 16, v210
	v_and_b32_e32 v241, 0xffff0000, v211
	v_lshlrev_b32_e32 v240, 16, v211
	v_and_b32_e32 v243, 0xffff0000, v212
	v_lshlrev_b32_e32 v242, 16, v212
	v_and_b32_e32 v245, 0xffff0000, v213
	v_lshlrev_b32_e32 v244, 16, v213
	v_pk_mul_f32 v[20:21], v[20:21], v[238:239]
	v_pk_mul_f32 v[22:23], v[22:23], v[240:241]
	v_pk_mul_f32 v[16:17], v[16:17], v[242:243]
	v_pk_mul_f32 v[18:19], v[18:19], v[244:245]
	v_cvt_pk_bf16_f32 v210, v20, v21
	v_cvt_pk_bf16_f32 v211, v22, v23
	v_cvt_pk_bf16_f32 v212, v16, v17
	v_cvt_pk_bf16_f32 v213, v18, v19
	global_store_dwordx4 v[144:145], v[210:213], off offset:256
	v_lshl_add_u64 v[144:145], v[144:145], 0, s[60:61]
	s_waitcnt vmcnt(15)
	v_pk_mul_f32 v[12:13], v[12:13], v[222:223]
	v_pk_mul_f32 v[14:15], v[14:15], v[224:225]
	v_pk_mul_f32 v[8:9], v[8:9], v[226:227]
	v_pk_mul_f32 v[10:11], v[10:11], v[228:229]
	v_and_b32_e32 v239, 0xffff0000, v214
	v_lshlrev_b32_e32 v238, 16, v214
	v_and_b32_e32 v241, 0xffff0000, v215
	v_lshlrev_b32_e32 v240, 16, v215
	v_and_b32_e32 v243, 0xffff0000, v216
	v_lshlrev_b32_e32 v242, 16, v216
	v_and_b32_e32 v245, 0xffff0000, v217
	v_lshlrev_b32_e32 v244, 16, v217
	v_pk_mul_f32 v[12:13], v[12:13], v[238:239]
	v_pk_mul_f32 v[14:15], v[14:15], v[240:241]
	v_pk_mul_f32 v[8:9], v[8:9], v[242:243]
	v_pk_mul_f32 v[10:11], v[10:11], v[244:245]
	v_cvt_pk_bf16_f32 v214, v12, v13
	v_cvt_pk_bf16_f32 v215, v14, v15
	v_cvt_pk_bf16_f32 v216, v8, v9
	v_cvt_pk_bf16_f32 v217, v10, v11
	global_store_dwordx4 v[144:145], v[214:217], off
	s_waitcnt vmcnt(15)
	v_pk_mul_f32 v[4:5], v[4:5], v[230:231]
	v_pk_mul_f32 v[6:7], v[6:7], v[232:233]
	v_pk_mul_f32 v[0:1], v[0:1], v[234:235]
	v_pk_mul_f32 v[2:3], v[2:3], v[236:237]
	v_and_b32_e32 v239, 0xffff0000, v218
	v_lshlrev_b32_e32 v238, 16, v218
	v_and_b32_e32 v241, 0xffff0000, v219
	v_lshlrev_b32_e32 v240, 16, v219
	v_and_b32_e32 v243, 0xffff0000, v220
	v_lshlrev_b32_e32 v242, 16, v220
	v_and_b32_e32 v245, 0xffff0000, v221
	v_lshlrev_b32_e32 v244, 16, v221
	v_pk_mul_f32 v[4:5], v[4:5], v[238:239]
	v_pk_mul_f32 v[6:7], v[6:7], v[240:241]
	v_pk_mul_f32 v[0:1], v[0:1], v[242:243]
	v_pk_mul_f32 v[2:3], v[2:3], v[244:245]
	v_cvt_pk_bf16_f32 v218, v4, v5
	v_cvt_pk_bf16_f32 v219, v6, v7
	v_cvt_pk_bf16_f32 v220, v0, v1
	v_cvt_pk_bf16_f32 v221, v2, v3
	global_store_dwordx4 v[144:145], v[218:221], off offset:256
	s_cbranch_vccz .LBB0_1385
	s_waitcnt vmcnt(0)
	s_cmpk_gt_u32 s30, 0xff
	s_cbranch_scc1 .LBB0_1396
	s_barrier
